# PJ tail round removed: last 32 SwiGLU tiles run on idle WGs 192-223 during PK with counter handoff; PK row blocks 40-47 wait before staging H cols >= 2304
# speedup vs baseline: 1.0102x; 1.0102x over previous
.LBB0_18:
	s_load_dwordx8 s[16:23], s[0:1], 0x100
	s_cmpk_eq_u32 s26, 0x100
	s_cselect_b32 s101, 1, 0
	s_lshl_b32 s41, s43, 3
	s_lshl_b32 s96, s26, 3
	v_mov_b32_e32 v248, 0x358637bd
	v_mov_b32_e32 v226, 0x3c0881c4
	s_waitcnt lgkmcnt(0)
	s_add_u32 s42, s22, 0x1c4d0000
	s_addc_u32 s17, s23, 0
	s_add_u32 s18, s22, 0x2690000
	s_addc_u32 s19, s23, 0
	s_add_u32 s33, s22, 0x2110000
	s_addc_u32 s34, s23, 0
	s_add_u32 s2, s22, 0x18390000
	s_addc_u32 s3, s23, 0
	v_writelane_b32 v249, s2, 8
	v_mov_b32_e32 v227, 0xbab64f3b
	v_mov_b32_e32 v194, 2.0
	v_writelane_b32 v249, s3, 9
	s_add_u32 s2, s22, 0x1a390000
	s_addc_u32 s3, s23, 0
	s_cmpk_lt_i32 s43, 0xc0
	v_writelane_b32 v249, s2, 10
	s_cselect_b64 s[36:37], -1, 0
	s_ashr_i32 s57, s43, 31
	v_writelane_b32 v249, s3, 11
	s_lshr_b32 s2, s57, 29
	s_add_i32 s2, s43, s2
	s_ashr_i32 s11, s2, 3
	s_and_b32 s2, s2, -8
	s_sub_i32 s12, s43, s2
	s_cmp_lt_i32 s12, 0
	s_cselect_b32 s2, 25, 24
	s_mul_i32 s14, s2, s12
	s_movk_i32 s2, 0x85
	s_cselect_b32 s6, s2, 0x84
	s_movk_i32 s2, 0xaf
	s_cselect_b32 s15, 13, 12
	s_cselect_b32 s13, s2, 0xae
	s_add_i32 s14, s14, s11
	s_ashr_i32 s2, s14, 31
	s_lshr_b32 s2, s2, 27
	s_add_i32 s2, s14, s2
	s_ashr_i32 s3, s2, 5
	s_and_b32 s2, s2, 0xffe0
	s_sub_i32 s7, s14, s2
	s_bfe_i32 s2, s7, 0x80000
	s_bfe_u32 s2, s2, 0x3000c
	s_add_i32 s8, s7, s2
	s_bfe_i32 s2, s8, 0x80000
	s_and_b32 s8, s8, 0xf8
	s_sub_i32 s7, s7, s8
	s_lshl_b32 s3, s3, 3
	s_sext_i32_i16 s9, s2
	s_sext_i32_i8 s7, s7
	s_lshr_b32 s2, s9, 3
	s_add_i32 s38, s3, s7
	s_ashr_i32 s3, s9, 3
	s_ashr_i32 s39, s38, 31
	s_mul_hi_i32 s9, s3, 0x160000
	v_writelane_b32 v249, s3, 12
	s_mul_i32 s16, s3, 0x160000
	s_bfe_i64 s[2:3], s[2:3], 0x100000
	s_add_u32 s44, s33, s16
	s_mul_i32 s8, s38, 0x160000
	v_writelane_b32 v249, s33, 13
	s_addc_u32 s45, s34, s9
	s_mul_hi_i32 s7, s38, 0x160000
	v_writelane_b32 v249, s34, 14
	s_add_u32 s8, s18, s8
	v_writelane_b32 v249, s18, 15
	s_addc_u32 s9, s19, s7
	s_mul_i32 s6, s6, s12
	v_writelane_b32 v249, s19, 16
	s_add_u32 s18, s44, 0xb0000
	s_addc_u32 s19, s45, 0
	v_writelane_b32 v249, s18, 17
	v_mov_b32_e32 v228, 1
	v_mov_b64_e32 v[230:231], 0xc0
	v_writelane_b32 v249, s19, 18
	s_add_u32 s18, s8, 0xb0000
	v_writelane_b32 v249, s8, 19
	s_addc_u32 s19, s9, 0
	v_mov_b64_e32 v[234:235], 0xbf
	v_writelane_b32 v249, s9, 20
	v_writelane_b32 v249, s18, 21
	s_add_u32 s8, s44, 0xb0080
	v_mov_b32_e32 v229, 0x1800
	v_writelane_b32 v249, s19, 22
	v_writelane_b32 v249, s44, 23
	s_addc_u32 s9, s45, 0
	s_ashr_i32 s60, s26, 31
	v_writelane_b32 v249, s45, 24
	v_writelane_b32 v249, s8, 25
	s_cmpk_gt_i32 s43, 0xbf
	v_mov_b32_e32 v236, 0x3000
	v_writelane_b32 v249, s9, 26
	s_cselect_b64 s[8:9], -1, 0
	s_add_i32 s7, s41, 0xfffffa00
	s_add_i32 s58, s96, 0xfffffa00
	s_add_u32 s72, s22, 0x1610000
	s_addc_u32 s16, s23, 0
	s_add_u32 s18, s22, 0x1410000
	s_addc_u32 s19, s23, 0
	s_add_u32 s34, s22, 0x1010000
	s_addc_u32 s35, s23, 0
	s_add_u32 s73, s22, 0xf90000
	s_addc_u32 s33, s23, 0
	s_add_u32 s40, s22, 0xf50000
	s_addc_u32 s44, s23, 0
	s_add_u32 s45, s22, 0xf10000
	s_addc_u32 s48, s23, 0
	s_add_u32 s50, s22, 0xe80000
	s_addc_u32 s51, s23, 0
	s_add_u32 s52, s22, 0xd490000
	v_writelane_b32 v249, s8, 27
	s_addc_u32 s53, s23, 0
	s_cmpk_lt_i32 s43, 0x420
	v_writelane_b32 v249, s9, 28
	v_writelane_b32 v249, s7, 29
	s_cselect_b64 s[8:9], -1, 0
	s_add_i32 s6, s6, s11
	s_cmp_eq_u32 s101, 0
	s_cbranch_scc1 .Lpj_first_orig
	s_lshl_b32 s6, s12, 7
	s_add_i32 s6, s6, s11
.Lpj_first_orig:
	v_writelane_b32 v249, s8, 30
	s_mul_hi_i32 s7, s6, 0x2e8ba2e9
	v_mov_b32_e32 v237, 0x4800
	v_writelane_b32 v249, s9, 31
	s_lshr_b32 s8, s7, 31
	s_ashr_i32 s7, s7, 5
	s_add_i32 s7, s7, s8
	s_mul_i32 s8, s7, 0xb0
	s_sub_i32 s6, s6, s8
	s_bfe_u32 s8, s6, 0x3001c
	s_add_i32 s8, s6, s8
	s_and_b32 s9, s8, 0xfff8
	s_sub_i32 s6, s6, s9
	s_lshl_b32 s7, s7, 3
	s_sext_i32_i16 s8, s8
	s_sext_i32_i16 s6, s6
	s_add_i32 s46, s7, s6
	s_ashr_i32 s6, s8, 3
	v_writelane_b32 v249, s6, 32
	s_lshr_b32 s6, s8, 3
	s_mov_b32 s8, s46
	s_ashr_i32 s47, s46, 31
	s_bfe_i64 s[6:7], s[6:7], 0x100000
	v_writelane_b32 v249, s8, 33
	s_lshl_b64 s[6:7], s[6:7], 19
	v_mov_b32_e32 v233, 0x7f800000
	v_writelane_b32 v249, s9, 34
	s_lshl_b64 s[8:9], s[46:47], 19
	s_add_u32 s6, s72, s6
	s_addc_u32 s7, s16, s7
	s_add_u32 s8, s52, s8
	s_addc_u32 s9, s53, s9
	s_add_u32 s46, s6, 0x40000
	v_writelane_b32 v249, s16, 35
	s_addc_u32 s47, s7, 0
	v_writelane_b32 v249, s46, 36
	v_not_b32_e32 v205, 63
	v_not_b32_e32 v238, 31
	v_writelane_b32 v249, s47, 37
	s_add_u32 s46, s8, 0x40000
	v_writelane_b32 v249, s8, 38
	s_addc_u32 s47, s9, 0
	v_mov_b32_e32 v239, 0x7fc00000
	v_writelane_b32 v249, s9, 39
	v_writelane_b32 v249, s46, 40
	s_add_u32 s8, s6, 0x40080
	s_movk_i32 s77, 0x84
	v_writelane_b32 v249, s47, 41
	v_writelane_b32 v249, s6, 42
	s_addc_u32 s9, s7, 0
	s_lshl_b64 s[2:3], s[2:3], 19
	v_writelane_b32 v249, s7, 43
	v_writelane_b32 v249, s8, 44
	s_mov_b32 s6, s38
	s_movk_i32 s76, 0x1a00
	v_writelane_b32 v249, s9, 45
	v_writelane_b32 v249, s6, 46
	s_movk_i32 s61, 0xc00
	s_mov_b64 s[74:75], 0x80
	v_writelane_b32 v249, s7, 47
	s_lshl_b64 s[6:7], s[38:39], 19
	s_add_u32 s8, s18, s2
	s_addc_u32 s9, s19, s3
	s_add_u32 s6, s52, s6
	s_addc_u32 s7, s53, s7
	v_writelane_b32 v249, s18, 48
	s_add_u32 s18, s8, 0x40000
	v_writelane_b32 v249, s19, 49
	s_addc_u32 s19, s9, 0
	v_writelane_b32 v249, s18, 50
	s_mul_i32 s2, s15, s12
	s_mul_i32 s12, s13, s12
	v_writelane_b32 v249, s19, 51
	s_add_u32 s18, s6, 0x40000
	v_writelane_b32 v249, s6, 52
	s_addc_u32 s19, s7, 0
	s_nop 0
	v_writelane_b32 v249, s7, 53
	v_writelane_b32 v249, s18, 54
	s_add_u32 s6, s8, 0x40080
	s_nop 0
	v_writelane_b32 v249, s19, 55
	v_writelane_b32 v249, s8, 56
	s_addc_u32 s7, s9, 0
	s_add_u32 s18, s22, 0x15390000
	v_writelane_b32 v249, s9, 57
	v_writelane_b32 v249, s6, 58
	s_addc_u32 s19, s23, 0
	s_nop 0
	v_writelane_b32 v249, s7, 59
	s_add_u32 s6, s22, 0x7490000
	s_addc_u32 s7, s23, 0
	s_lshr_b32 s3, s57, 30
	v_writelane_b32 v249, s6, 60
	s_add_i32 s3, s43, s3
	s_ashr_i32 s38, s3, 2
	v_writelane_b32 v249, s7, 61
	s_and_b32 s6, s3, -4
	s_sub_i32 s54, s43, s6
	s_cmpk_lt_i32 s43, 0x100
	s_cselect_b64 s[6:7], -1, 0
	v_writelane_b32 v249, s6, 62
	s_nop 1
	v_writelane_b32 v249, s7, 63
	s_add_u32 s6, s22, 0xfc10000
	s_addc_u32 s7, s23, 0
	v_writelane_b32 v250, s6, 0
	s_nop 1
	v_writelane_b32 v250, s7, 1
	s_add_u32 s6, s22, 0x1c518000
	s_addc_u32 s7, s23, 0
	v_writelane_b32 v250, s6, 2
	s_nop 1
	v_writelane_b32 v250, s7, 3
	s_add_u32 s6, s22, 0x12810000
	s_addc_u32 s7, s23, 0
	v_writelane_b32 v250, s6, 4
	s_nop 1
	v_writelane_b32 v250, s7, 5
	s_add_u32 s6, s22, 0x11b10000
	s_addc_u32 s7, s23, 0
	s_add_u32 s46, s22, 0xec90000
	s_addc_u32 s47, s23, 0
	v_writelane_b32 v250, s6, 6
	s_cmpk_lt_i32 s43, 0x60
	s_nop 0
	v_writelane_b32 v250, s7, 7
	s_cselect_b64 s[6:7], -1, 0
	s_add_i32 s2, s2, s11
	s_ashr_i32 s3, s2, 31
	s_lshr_b32 s3, s3, 28
	v_writelane_b32 v250, s6, 8
	s_add_i32 s3, s2, s3
	s_nop 0
	v_writelane_b32 v250, s7, 9
	s_and_b32 s6, s3, 0xfff0
	s_sub_i32 s2, s2, s6
	s_bfe_i32 s6, s2, 0x80000
	s_bfe_u32 s6, s6, 0x3000c
	s_add_i32 s6, s2, s6
	s_and_b32 s7, s6, 0xf8
	s_sub_i32 s2, s2, s7
	s_ashr_i32 s3, s3, 4
	s_bfe_i32 s6, s6, 0x80000
	s_lshl_b32 s3, s3, 3
	s_sext_i32_i16 s6, s6
	s_sext_i32_i8 s2, s2
	s_add_i32 s8, s3, s2
	s_ashr_i32 s2, s6, 3
	v_writelane_b32 v250, s2, 10
	s_lshr_b32 s2, s6, 3
	s_mov_b32 s6, s8
	s_ashr_i32 s9, s8, 31
	s_bfe_i64 s[2:3], s[2:3], 0x100000
	v_writelane_b32 v250, s6, 11
	s_lshl_b64 s[2:3], s[2:3], 18
	s_nop 0
	v_writelane_b32 v250, s7, 12
	s_lshl_b64 s[6:7], s[8:9], 18
	s_add_u32 s2, s73, s2
	s_addc_u32 s3, s33, s3
	s_add_u32 s6, s46, s6
	s_addc_u32 s7, s47, s7
	s_add_u32 s8, s2, 0x20000
	v_writelane_b32 v250, s33, 13
	s_addc_u32 s9, s3, 0
	v_writelane_b32 v250, s8, 14
	s_nop 1
	v_writelane_b32 v250, s9, 15
	s_add_u32 s8, s6, 0x20000
	v_writelane_b32 v250, s6, 16
	s_addc_u32 s9, s7, 0
	s_nop 0
	v_writelane_b32 v250, s7, 17
	v_writelane_b32 v250, s8, 18
	s_add_u32 s6, s2, 0x20080
	s_nop 0
	v_writelane_b32 v250, s9, 19
	v_writelane_b32 v250, s2, 20
	s_addc_u32 s7, s3, 0
	s_nop 0
	v_writelane_b32 v250, s3, 21
	v_writelane_b32 v250, s6, 22
	s_add_u32 s2, s22, 0x10e10000
	s_addc_u32 s3, s23, 0
	v_writelane_b32 v250, s7, 23
	v_writelane_b32 v250, s2, 24
	s_nop 1
	v_writelane_b32 v250, s3, 25
	s_add_u32 s2, s22, 0x15f90000
	v_writelane_b32 v250, s2, 26
	s_addc_u32 s2, s23, 0
	s_sub_i32 s15, s26, 64
	s_sub_i32 s16, s43, 64
	s_cmp_lt_i32 s43, 64
	v_writelane_b32 v250, s2, 27
	s_cselect_b64 s[2:3], -1, 0
	s_cmpk_lt_i32 s26, 0x41
	s_cselect_b64 s[8:9], -1, 0
	s_or_b64 s[2:3], s[2:3], s[8:9]
	s_cmp_gt_i32 s43, 31
	s_cselect_b64 s[6:7], -1, 0
	s_cmp_gt_i32 s26, 64
	v_writelane_b32 v250, s2, 28
	s_cselect_b64 s[62:63], -1, 0
	v_cndmask_b32_e64 v0, 0, 1, s[6:7]
	v_writelane_b32 v250, s3, 29
	s_and_b64 s[2:3], s[62:63], exec
	s_cselect_b32 s49, s15, s26
	s_cselect_b32 s15, s16, s43
	s_cselect_b32 s65, 32, s26
	v_writelane_b32 v250, s62, 30
	s_and_b64 s[2:3], s[6:7], s[62:63]
	s_and_b64 s[2:3], s[2:3], exec
	s_cselect_b32 s2, 0xffffffe0, 0
	s_add_i32 s6, s2, s43
	s_add_u32 s2, s22, 0x1b4d0000
	v_writelane_b32 v250, s63, 31
	s_addc_u32 s3, s23, 0
	v_writelane_b32 v250, s2, 32
	s_nop 1
	v_writelane_b32 v250, s3, 33
	s_add_u32 s2, s22, 0x14b90000
	s_addc_u32 s3, s23, 0
	v_writelane_b32 v250, s2, 34
	s_cmp_lt_i32 s6, 32
	s_nop 0
	v_writelane_b32 v250, s3, 35
	s_cselect_b64 s[2:3], -1, 0
	v_writelane_b32 v250, s2, 36
	s_nop 1
	v_writelane_b32 v250, s3, 37
	s_ashr_i32 s2, s6, 31
	v_writelane_b32 v250, s2, 38
	s_lshr_b32 s2, s2, 28
	s_add_i32 s2, s6, s2
	s_and_b32 s3, s2, 0xfff0
	s_sub_i32 s3, s6, s3
	v_writelane_b32 v250, s6, 39
	s_bfe_u32 s6, s3, 0x10007
	s_add_i32 s6, s3, s6
	s_bfe_i32 s7, s6, 0x80000
	s_sext_i32_i16 s7, s7
	s_ashr_i32 s62, s2, 4
	s_ashr_i32 s2, s7, 1
	s_and_b32 s6, s6, 0xfffe
	v_writelane_b32 v250, s2, 40
	s_lshr_b32 s2, s7, 1
	s_sub_i32 s6, s3, s6
	s_bfe_i64 s[2:3], s[2:3], 0x100000
	s_lshl_b64 s[2:3], s[2:3], 21
	v_writelane_b32 v250, s2, 41
	s_ashr_i32 s63, s62, 31
	s_nop 0
	v_writelane_b32 v250, s3, 42
	s_bfe_i64 s[2:3], s[6:7], 0x80000
	s_lshl_b64 s[2:3], s[2:3], 22
	v_writelane_b32 v250, s2, 43
	s_sext_i32_i8 s6, s6
	s_nop 0
	v_writelane_b32 v250, s3, 44
	s_ashr_i32 s2, s65, 31
	v_writelane_b32 v250, s2, 45
	s_mov_b32 s2, s62
	v_writelane_b32 v250, s2, 46
	s_nop 1
	v_writelane_b32 v250, s3, 47
	s_lshl_b64 s[2:3], s[62:63], 13
	v_writelane_b32 v250, s2, 48
	s_cmp_gt_i32 s43, 63
	s_nop 0
	v_writelane_b32 v250, s3, 49
	s_cselect_b64 s[2:3], -1, 0
	s_or_b64 s[2:3], s[2:3], s[8:9]
	v_writelane_b32 v250, s2, 50
	s_cmpk_lt_i32 s15, 0x90
	s_nop 0
	v_writelane_b32 v250, s3, 51
	s_cselect_b64 s[2:3], -1, 0
	v_writelane_b32 v250, s2, 52
	s_nop 1
	v_writelane_b32 v250, s3, 53
	s_ashr_i32 s2, s15, 31
	v_writelane_b32 v250, s2, 54
	s_lshr_b32 s2, s2, 29
	s_add_i32 s2, s15, s2
	s_ashr_i32 s3, s2, 3
	s_and_b32 s2, s2, -8
	s_sub_i32 s2, s15, s2
	s_cmp_lt_i32 s2, 0
	s_cselect_b32 s7, 19, 18
	s_mul_i32 s2, s7, s2
	s_add_i32 s2, s2, s3
	s_mul_hi_i32 s3, s2, 0x2aaaaaab
	s_lshr_b32 s7, s3, 31
	s_ashr_i32 s3, s3, 2
	s_add_i32 s3, s3, s7
	s_mul_i32 s7, s3, 24
	s_sub_i32 s2, s2, s7
	s_bfe_i32 s7, s2, 0x80000
	s_bfe_u32 s7, s7, 0x3000c
	s_add_i32 s7, s2, s7
	s_and_b32 s8, s7, 0xf8
	s_sub_i32 s2, s2, s8
	s_lshl_b32 s3, s3, 3
	s_sext_i32_i8 s2, s2
	s_add_i32 s8, s3, s2
	s_bfe_i32 s2, s7, 0x80000
	s_sext_i32_i16 s2, s2
	s_ashr_i32 s3, s2, 3
	s_mul_hi_i32 s2, s3, 0x30000
	v_writelane_b32 v250, s3, 55
	s_mul_i32 s3, s3, 0x30000
	s_add_u32 s62, s50, s3
	s_addc_u32 s63, s51, s2
	s_mul_i32 s3, s8, 0x30000
	s_mul_hi_i32 s2, s8, 0x30000
	v_writelane_b32 v250, s8, 56
	s_add_u32 s8, s46, s3
	v_writelane_b32 v250, s46, 57
	s_addc_u32 s9, s47, s2
	s_add_u32 s2, s62, 0x18000
	v_writelane_b32 v250, s47, 58
	s_addc_u32 s3, s63, 0
	v_writelane_b32 v250, s2, 59
	s_nop 1
	v_writelane_b32 v250, s3, 60
	s_add_u32 s2, s8, 0x18000
	v_writelane_b32 v250, s8, 61
	s_addc_u32 s3, s9, 0
	s_nop 0
	v_writelane_b32 v250, s9, 62
	v_writelane_b32 v250, s2, 63
	s_nop 1
	v_writelane_b32 v251, s3, 0
	s_add_u32 s2, s62, 0x18080
	v_writelane_b32 v251, s62, 1
	s_addc_u32 s3, s63, 0
	s_nop 0
	v_writelane_b32 v251, s63, 2
	v_writelane_b32 v251, s2, 3
	s_nop 1
	v_writelane_b32 v251, s3, 4
	s_ashr_i32 s2, s49, 31
	v_writelane_b32 v251, s2, 5
	s_add_i32 s2, s49, s15
	s_add_u32 s62, s22, 0xf590000
	s_addc_u32 s63, s23, 0
	s_add_i32 s9, s2, s49
	s_add_u32 s46, s22, 0x1b490000
	s_addc_u32 s47, s23, 0
	s_add_u32 s66, s22, 0x13b90000
	s_addc_u32 s67, s23, 0
	s_add_u32 s68, s22, 0x1b4b0000
	s_addc_u32 s69, s23, 0
	v_writelane_b32 v251, s68, 6
	s_nop 1
	v_writelane_b32 v251, s69, 7
	s_add_u32 s68, s22, 0x1b490080
	s_addc_u32 s69, s23, 0
	v_writelane_b32 v251, s68, 8
	s_lshl_b32 s3, s15, 3
	s_nop 0
	v_writelane_b32 v251, s69, 9
	v_writelane_b32 v251, s15, 10
	v_writelane_b32 v251, s3, 11
	s_lshl_b32 s3, s49, 3
	s_add_u32 s68, s22, 0x1c558000
	v_writelane_b32 v251, s3, 12
	s_addc_u32 s69, s23, 0
	v_writelane_b32 v251, s68, 13
	s_mul_hi_i32 s3, s14, 0x2aaaaaab
	s_nop 0
	v_writelane_b32 v251, s69, 14
	s_add_u32 s68, s22, 0x1c598000
	s_addc_u32 s69, s23, 0
	v_writelane_b32 v251, s68, 15
	s_nop 1
	v_writelane_b32 v251, s69, 16
	s_add_u32 s68, s22, 0x1c698000
	s_addc_u32 s69, s23, 0
	v_writelane_b32 v251, s68, 17
	s_nop 1
	v_writelane_b32 v251, s69, 18
	s_add_u32 s68, s22, 0x1c798000
	s_addc_u32 s69, s23, 0
	v_writelane_b32 v251, s68, 19
	s_nop 1
	v_writelane_b32 v251, s69, 20
	s_add_u32 s68, s20, 0x5400000
	s_addc_u32 s69, s21, 0
	v_writelane_b32 v251, s68, 21
	s_nop 1
	v_writelane_b32 v251, s69, 22
	s_add_u32 s68, s22, 0x1b390000
	s_addc_u32 s69, s23, 0
	v_writelane_b32 v251, s68, 23
	s_add_u32 s7, s22, 0x2690400
	s_nop 0
	v_writelane_b32 v251, s69, 24
	v_writelane_b32 v251, s7, 25
	s_addc_u32 s7, s23, 0
	v_writelane_b32 v251, s7, 26
	s_lshr_b32 s7, s3, 31
	s_ashr_i32 s3, s3, 6
	s_add_i32 s3, s3, s7
	s_mul_i32 s7, s3, 0x180
	s_lshl_b32 s3, s3, 3
	s_sub_i32 s8, 4, s3
	s_sub_i32 s7, s14, s7
	s_min_u32 s8, s8, 8
	s_add_u32 s14, s20, 0x3000000
	s_addc_u32 s15, s21, 0
	v_writelane_b32 v251, s14, 27
	s_nop 1
	v_writelane_b32 v251, s15, 28
	s_add_u32 s14, s20, 0x5000000
	s_addc_u32 s15, s21, 0
	v_writelane_b32 v251, s14, 29
	s_cmpk_lt_i32 s43, 0x570
	s_nop 0
	v_writelane_b32 v251, s15, 30
	s_cselect_b64 s[14:15], -1, 0
	s_add_i32 s12, s12, s11
	s_mul_hi_i32 s11, s12, 0x8d3dcb09
	s_add_i32 s11, s11, s12
	s_lshr_b32 s13, s11, 31
	s_ashr_i32 s11, s11, 7
	s_add_i32 s11, s11, s13
	s_mul_i32 s13, s11, 0xe8
	s_sub_i32 s12, s12, s13
	s_bfe_u32 s13, s12, 0x3001c
	v_writelane_b32 v251, s14, 31
	s_add_i32 s13, s12, s13
	s_lshl_b32 s11, s11, 3
	v_writelane_b32 v251, s15, 32
	s_and_b32 s14, s13, 0xfff8
	s_sub_i32 s12, s12, s14
	s_sext_i32_i16 s13, s13
	s_sext_i32_i16 s12, s12
	s_add_i32 s68, s11, s12
	s_ashr_i32 s11, s13, 3
	v_writelane_b32 v251, s11, 33
	s_lshr_b32 s12, s13, 3
	s_mov_b32 s14, s68
	s_ashr_i32 s69, s68, 31
	s_bfe_i64 s[12:13], s[12:13], 0x100000
	v_writelane_b32 v251, s14, 34
	s_lshl_b64 s[12:13], s[12:13], 19
	s_nop 0
	v_writelane_b32 v251, s15, 35
	s_lshl_b64 s[14:15], s[68:69], 19
	s_add_u32 s12, s22, s12
	s_addc_u32 s13, s23, s13
	s_add_u32 s14, s52, s14
	v_writelane_b32 v251, s52, 36
	s_addc_u32 s15, s53, s15
	s_nop 0
	v_writelane_b32 v251, s53, 37
	s_add_u32 s52, s12, 0x40000
	s_addc_u32 s53, s13, 0
	v_writelane_b32 v251, s52, 38
	s_nop 1
	v_writelane_b32 v251, s53, 39
	s_add_u32 s52, s14, 0x40000
	v_writelane_b32 v251, s14, 40
	s_addc_u32 s53, s15, 0
	s_nop 0
	v_writelane_b32 v251, s15, 41
	v_writelane_b32 v251, s52, 42
	s_add_u32 s14, s12, 0x40080
	s_nop 0
	v_writelane_b32 v251, s53, 43
	v_writelane_b32 v251, s12, 44
	s_addc_u32 s15, s13, 0
	s_cmpk_gt_i32 s26, 0xc0
	v_writelane_b32 v251, s13, 45
	v_writelane_b32 v251, s14, 46
	s_cselect_b64 s[12:13], -1, 0
	s_nop 0
	v_writelane_b32 v251, s15, 47
	v_writelane_b32 v251, s12, 48
	s_nop 1
	v_writelane_b32 v251, s13, 49
	s_and_b64 s[12:13], s[12:13], exec
	s_cselect_b32 s11, 0x20e0, 0
	v_writelane_b32 v251, s11, 50
	s_lshl_b32 s11, s43, 9
	s_lshl_b32 s70, s26, 9
	s_cmpk_lt_i32 s43, 0x180
	v_writelane_b32 v251, s11, 51
	s_cselect_b64 s[12:13], -1, 0
	v_writelane_b32 v251, s12, 52
	s_nop 1
	v_writelane_b32 v251, s13, 53
	s_add_u32 s12, s22, 0x1c818200
	s_addc_u32 s13, s23, 0
	v_writelane_b32 v251, s12, 54
	s_nop 1
	v_writelane_b32 v251, s13, 55
	s_add_u32 s12, s22, 0x1c818400
	s_addc_u32 s13, s23, 0
	v_writelane_b32 v251, s12, 56
	s_nop 1
	v_writelane_b32 v251, s13, 57
	s_add_u32 s12, s22, 0x1c818500
	s_addc_u32 s13, s23, 0
	v_writelane_b32 v251, s12, 58
	s_nop 1
	v_writelane_b32 v251, s13, 59
	s_add_u32 s12, s22, 0x1c818600
	s_addc_u32 s13, s23, 0
	v_writelane_b32 v251, s12, 60
	s_nop 1
	v_writelane_b32 v251, s13, 61
	s_add_u32 s12, s22, 0x1c818700
	s_addc_u32 s13, s23, 0
	v_writelane_b32 v251, s12, 62
	s_nop 1
	v_writelane_b32 v251, s13, 63
	s_add_u32 s12, s22, 0x1c818800
	s_addc_u32 s13, s23, 0
	v_writelane_b32 v252, s12, 0
	s_nop 1
	v_writelane_b32 v252, s13, 1
	s_add_u32 s12, s22, 0x1c818900
	s_addc_u32 s13, s23, 0
	v_writelane_b32 v252, s12, 2
	s_nop 1
	v_writelane_b32 v252, s13, 3
	s_add_u32 s12, s22, 0x1c818a00
	s_addc_u32 s13, s23, 0
	v_writelane_b32 v252, s12, 4
	s_nop 1
	v_writelane_b32 v252, s13, 5
	s_add_u32 s12, s22, 0x1c818b00
	s_addc_u32 s13, s23, 0
	v_writelane_b32 v252, s12, 6
	s_nop 1
	v_writelane_b32 v252, s13, 7
	s_add_u32 s12, s22, 0x1c818c00
	s_addc_u32 s13, s23, 0
	v_writelane_b32 v252, s12, 8
	s_nop 1
	v_writelane_b32 v252, s13, 9
	s_add_u32 s12, s22, 0x1c818d00
	s_addc_u32 s13, s23, 0
	v_writelane_b32 v252, s12, 10
	s_nop 1
	v_writelane_b32 v252, s13, 11
	s_add_u32 s12, s22, 0x1c818e00
	s_addc_u32 s13, s23, 0
	v_writelane_b32 v252, s12, 12
	s_nop 1
	v_writelane_b32 v252, s13, 13
	s_add_u32 s12, s22, 0x1c818f00
	s_addc_u32 s13, s23, 0
	v_writelane_b32 v252, s12, 14
	s_nop 1
	v_writelane_b32 v252, s13, 15
	s_add_u32 s12, s22, 0x1c819000
	s_addc_u32 s13, s23, 0
	v_writelane_b32 v252, s12, 16
	s_nop 1
	v_writelane_b32 v252, s13, 17
	s_add_u32 s12, s22, 0x1c819100
	s_addc_u32 s13, s23, 0
	v_writelane_b32 v252, s12, 18
	s_nop 1
	v_writelane_b32 v252, s13, 19
	s_add_u32 s12, s22, 0x1c819200
	s_addc_u32 s13, s23, 0
	v_writelane_b32 v252, s12, 20
	s_nop 1
	v_writelane_b32 v252, s13, 21
	s_add_u32 s12, s22, 0x1c819300
	s_addc_u32 s13, s23, 0
	v_writelane_b32 v252, s12, 22
	s_cmp_eq_u32 s10, 15
	s_nop 0
	v_writelane_b32 v252, s13, 23
	s_cselect_b64 s[12:13], -1, 0
	v_writelane_b32 v252, s12, 24
	s_cmp_eq_u32 s10, 14
	s_nop 0
	v_writelane_b32 v252, s13, 25
	s_cselect_b64 s[12:13], -1, 0
	v_writelane_b32 v252, s12, 26
	s_cmp_eq_u32 s10, 13
	s_nop 0
	v_writelane_b32 v252, s13, 27
	s_cselect_b64 s[12:13], -1, 0
	v_writelane_b32 v252, s12, 28
	s_cmp_eq_u32 s10, 12
	s_nop 0
	v_writelane_b32 v252, s13, 29
	s_cselect_b64 s[12:13], -1, 0
	v_writelane_b32 v252, s12, 30
	s_cmp_eq_u32 s10, 11
	s_nop 0
	v_writelane_b32 v252, s13, 31
	s_cselect_b64 s[12:13], -1, 0
	v_writelane_b32 v252, s12, 32
	s_cmp_eq_u32 s10, 10
	s_nop 0
	v_writelane_b32 v252, s13, 33
	s_cselect_b64 s[12:13], -1, 0
	v_writelane_b32 v252, s12, 34
	s_cmp_eq_u32 s10, 9
	s_nop 0
	v_writelane_b32 v252, s13, 35
	s_cselect_b64 s[12:13], -1, 0
	v_writelane_b32 v252, s12, 36
	s_cmp_eq_u32 s10, 8
	s_nop 0
	v_writelane_b32 v252, s13, 37
	s_cselect_b64 s[12:13], -1, 0
	v_writelane_b32 v252, s12, 38
	s_cmp_eq_u32 s10, 7
	s_nop 0
	v_writelane_b32 v252, s13, 39
	s_cselect_b64 s[12:13], -1, 0
	v_writelane_b32 v252, s12, 40
	s_cmp_eq_u32 s10, 6
	s_nop 0
	v_writelane_b32 v252, s13, 41
	s_cselect_b64 s[12:13], -1, 0
	v_writelane_b32 v252, s12, 42
	s_cmp_eq_u32 s10, 5
	s_nop 0
	v_writelane_b32 v252, s13, 43
	s_cselect_b64 s[12:13], -1, 0
	v_writelane_b32 v252, s12, 44
	s_cmp_eq_u32 s10, 4
	s_nop 0
	v_writelane_b32 v252, s13, 45
	s_cselect_b64 s[12:13], -1, 0
	v_writelane_b32 v252, s12, 46
	s_cmp_eq_u32 s10, 3
	s_nop 0
	v_writelane_b32 v252, s13, 47
	s_cselect_b64 s[12:13], -1, 0
	v_writelane_b32 v252, s12, 48
	s_cmp_eq_u32 s10, 2
	s_nop 0
	v_writelane_b32 v252, s13, 49
	s_cselect_b64 s[12:13], -1, 0
	v_writelane_b32 v252, s12, 50
	s_cmp_eq_u32 s10, 1
	s_nop 0
	v_writelane_b32 v252, s13, 51
	s_cselect_b64 s[12:13], -1, 0
	v_writelane_b32 v252, s12, 52
	s_cmp_eq_u32 s10, 0
	s_nop 0
	v_writelane_b32 v252, s13, 53
	s_cselect_b64 s[12:13], -1, 0
	s_lshl_b32 s10, s10, 8
	s_add_u32 s4, s4, s10
	s_addc_u32 s5, s5, 0
	v_writelane_b32 v252, s12, 54
	s_add_u32 s10, s4, 0x1400
	s_addc_u32 s11, s5, 0
	v_writelane_b32 v252, s13, 55
	v_writelane_b32 v252, s10, 56
	s_add_u32 s4, s4, 0x2400
	s_addc_u32 s5, s5, 0
	v_writelane_b32 v252, s11, 57
	v_writelane_b32 v252, s4, 58
	s_mov_b32 s10, s54
	s_nop 0
	v_writelane_b32 v252, s5, 59
	s_add_u32 s4, s22, 0x1c81b400
	s_addc_u32 s5, s23, 0
	v_writelane_b32 v252, s4, 60
	s_nop 1
	v_writelane_b32 v252, s5, 61
	s_add_u32 s4, s22, 0x1c81b500
	s_addc_u32 s5, s23, 0
	v_writelane_b32 v252, s4, 62
	s_ashr_i32 s39, s38, 31
	s_ashr_i32 s55, s54, 31
	v_writelane_b32 v252, s5, 63
	s_mov_b32 s4, s38
	v_writelane_b32 v253, s4, 0
	s_nop 1
	v_writelane_b32 v253, s5, 1
	v_writelane_b32 v253, s10, 2
	s_lshl_b64 s[4:5], s[38:39], 18
	s_nop 0
	v_writelane_b32 v253, s11, 3
	s_lshl_b64 s[10:11], s[54:55], 18
	s_add_u32 s10, s34, s10
	v_writelane_b32 v253, s34, 4
	s_addc_u32 s11, s35, s11
	v_writelane_b32 v253, s35, 5
	s_add_u32 s4, s18, s4
	v_writelane_b32 v253, s18, 6
	s_addc_u32 s5, s19, s5
	s_add_u32 s12, s10, 0x20000
	v_writelane_b32 v253, s19, 7
	s_addc_u32 s13, s11, 0
	v_writelane_b32 v253, s12, 8
	s_mov_b32 s35, 0x3fb8aa3b
	s_mov_b32 s34, 0xc2ce8ed0
	v_writelane_b32 v253, s13, 9
	s_add_u32 s12, s4, 0x20000
	v_writelane_b32 v253, s4, 10
	s_addc_u32 s13, s5, 0
	s_nop 0
	v_writelane_b32 v253, s5, 11
	v_writelane_b32 v253, s12, 12
	s_add_u32 s4, s10, 0x20080
	s_nop 0
	v_writelane_b32 v253, s13, 13
	v_writelane_b32 v253, s10, 14
	s_addc_u32 s5, s11, 0
	s_nop 0
	v_writelane_b32 v253, s11, 15
	v_writelane_b32 v253, s4, 16
	s_nop 1
	v_writelane_b32 v253, s5, 17
	s_abs_i32 s5, s49
	v_cvt_f32_u32_e32 v1, s5
	s_sub_i32 s4, 0, s5
	v_writelane_b32 v253, s49, 18
	v_rcp_iflag_f32_e32 v1, v1
	s_nop 0
	v_mul_f32_e32 v1, 0x4f7ffffe, v1
	v_cvt_u32_f32_e32 v1, v1
	s_nop 0
	v_readfirstlane_b32 s10, v1
	s_mul_i32 s4, s4, s10
	s_mul_hi_u32 s4, s10, s4
	s_add_i32 s10, s10, s4
	s_mul_hi_u32 s4, s10, 0x90
	s_mul_i32 s4, s4, s5
	s_sub_i32 s4, 0x90, s4
	s_sub_i32 s11, s4, s5
	s_cmp_ge_u32 s4, s5
	s_cselect_b32 s4, s11, s4
	s_sub_i32 s11, s4, s5
	s_cmp_ge_u32 s4, s5
	s_cselect_b32 s4, s11, s4
	s_sub_i32 s2, s2, s4
	s_abs_i32 s4, s2
	s_mul_hi_u32 s11, s4, s10
	s_mul_i32 s11, s11, s5
	s_sub_i32 s4, s4, s11
	s_ashr_i32 s2, s2, 31
	s_sub_i32 s11, s4, s5
	s_cmp_ge_u32 s4, s5
	s_cselect_b32 s4, s11, s4
	s_sub_i32 s11, s4, s5
	s_cmp_ge_u32 s4, s5
	s_cselect_b32 s4, s11, s4
	s_xor_b32 s4, s4, s2
	s_sub_i32 s11, s4, s2
	s_cmpk_lt_i32 s11, 0x68
	s_cselect_b64 s[12:13], -1, 0
	v_writelane_b32 v253, s12, 19
	s_ashr_i32 s2, s11, 31
	s_nop 0
	v_writelane_b32 v253, s13, 20
	v_writelane_b32 v253, s2, 21
	s_lshr_b32 s2, s2, 29
	s_add_i32 s2, s11, s2
	s_ashr_i32 s4, s2, 3
	s_and_b32 s2, s2, -8
	s_sub_i32 s2, s11, s2
	s_cmp_lt_i32 s2, 0
	v_writelane_b32 v253, s11, 22
	s_cselect_b32 s11, 14, 13
	s_mul_i32 s2, s11, s2
	s_add_i32 s2, s2, s4
	s_ashr_i32 s4, s2, 31
	s_lshr_b32 s4, s4, 28
	s_add_i32 s4, s2, s4
	s_and_b32 s11, s4, -16
	s_ashr_i32 s4, s4, 4
	s_sub_i32 s2, s2, s11
	s_lshl_b32 s11, s4, 3
	s_sub_i32 s4, 52, s11
	s_min_u32 s14, s4, 8
	v_cvt_f32_ubyte0_e32 v2, s14
	v_cvt_f32_i32_e32 v1, s2
	v_rcp_iflag_f32_e32 v3, v2
	s_ashr_i32 s4, s2, 30
	s_or_b32 s4, s4, 1
	v_mul_f32_e32 v3, v1, v3
	v_trunc_f32_e32 v3, v3
	v_fma_f32 v1, -v3, v2, v1
	v_cmp_ge_f32_e64 s[12:13], |v1|, v2
	v_cvt_i32_f32_e32 v1, v3
	s_and_b64 s[12:13], s[12:13], exec
	s_cselect_b32 s4, s4, 0
	v_readfirstlane_b32 s12, v1
	s_add_i32 s4, s12, s4
	s_mul_i32 s12, s4, s14
	s_sub_i32 s2, s2, s12
	s_sext_i32_i8 s2, s2
	s_add_i32 s14, s11, s2
	s_ashr_i32 s15, s14, 31
	s_bfe_i64 s[12:13], s[4:5], 0x80000
	s_lshl_b64 s[12:13], s[12:13], 17
	s_mov_b32 s2, s14
	s_lshl_b64 s[14:15], s[14:15], 17
	s_add_u32 s12, s45, s12
	s_addc_u32 s13, s48, s13
	v_writelane_b32 v253, s2, 23
	s_add_u32 s14, s62, s14
	s_addc_u32 s15, s63, s15
	v_writelane_b32 v253, s3, 24
	v_writelane_b32 v253, s45, 25
	s_add_u32 s18, s12, 0x10000
	v_writelane_b32 v253, s48, 26
	s_addc_u32 s19, s13, 0
	v_writelane_b32 v253, s18, 27
	s_mul_hi_u32 s2, s10, 0xf8
	s_mul_i32 s2, s2, s5
	v_writelane_b32 v253, s19, 28
	s_add_u32 s18, s14, 0x10000
	v_writelane_b32 v253, s14, 29
	s_addc_u32 s19, s15, 0
	s_sext_i32_i8 s4, s4
	v_writelane_b32 v253, s15, 30
	v_writelane_b32 v253, s18, 31
	s_add_u32 s14, s12, 0x10080
	s_movk_i32 s48, 0x600
	v_writelane_b32 v253, s19, 32
	v_writelane_b32 v253, s12, 33
	s_addc_u32 s15, s13, 0
	s_sub_i32 s2, 0xf8, s2
	s_sub_i32 s11, s2, s5
	s_cmp_ge_u32 s2, s5
	s_cselect_b32 s2, s11, s2
	s_sub_i32 s11, s2, s5
	s_cmp_ge_u32 s2, s5
	s_cselect_b32 s2, s11, s2
	s_sub_i32 s2, s9, s2
	s_abs_i32 s11, s2
	v_writelane_b32 v253, s13, 34
	s_mul_hi_u32 s12, s11, s10
	s_mul_i32 s12, s12, s5
	s_sub_i32 s11, s11, s12
	s_ashr_i32 s2, s2, 31
	s_sub_i32 s12, s11, s5
	s_cmp_ge_u32 s11, s5
	s_cselect_b32 s11, s12, s11
	s_sub_i32 s12, s11, s5
	s_cmp_ge_u32 s11, s5
	s_cselect_b32 s11, s12, s11
	s_xor_b32 s11, s11, s2
	s_sub_i32 s12, s11, s2
	v_writelane_b32 v253, s14, 35
	s_cmpk_lt_i32 s12, 0x68
	s_nop 0
	v_writelane_b32 v253, s15, 36
	s_cselect_b64 s[14:15], -1, 0
	v_writelane_b32 v253, s14, 37
	s_ashr_i32 s2, s12, 31
	s_nop 0
	v_writelane_b32 v253, s15, 38
	v_writelane_b32 v253, s2, 39
	s_lshr_b32 s2, s2, 29
	s_add_i32 s2, s12, s2
	s_ashr_i32 s11, s2, 3
	s_and_b32 s2, s2, -8
	s_sub_i32 s2, s12, s2
	s_cmp_lt_i32 s2, 0
	v_writelane_b32 v253, s12, 40
	s_cselect_b32 s12, 14, 13
	s_mul_i32 s2, s12, s2
	s_add_i32 s2, s2, s11
	s_mul_hi_i32 s11, s2, 0x4ec4ec4f
	s_lshr_b32 s12, s11, 31
	s_ashr_i32 s11, s11, 7
	s_add_i32 s11, s11, s12
	s_mul_i32 s12, s11, 0x1a0
	s_lshl_b32 s11, s11, 3
	s_sub_i32 s14, s2, s12
	s_sub_i32 s2, 2, s11
	s_min_u32 s15, s2, 8
	v_cvt_f32_ubyte0_e32 v2, s15
	v_cvt_f32_i32_e32 v1, s14
	v_rcp_iflag_f32_e32 v3, v2
	s_ashr_i32 s2, s14, 30
	s_or_b32 s2, s2, 1
	v_mul_f32_e32 v3, v1, v3
	v_trunc_f32_e32 v3, v3
	v_fma_f32 v1, -v3, v2, v1
	v_cmp_ge_f32_e64 s[12:13], |v1|, v2
	v_cvt_i32_f32_e32 v1, v3
	s_and_b64 s[12:13], s[12:13], exec
	s_cselect_b32 s2, s2, 0
	v_cvt_f32_ubyte0_e32 v2, s8
	v_readfirstlane_b32 s12, v1
	s_add_i32 s2, s12, s2
	s_mul_i32 s12, s2, s15
	s_sub_i32 s12, s14, s12
	s_sext_i32_i16 s12, s12
	s_add_i32 s18, s11, s12
	s_mov_b32 s14, s18
	s_ashr_i32 s19, s18, 31
	s_bfe_i64 s[12:13], s[2:3], 0x100000
	v_writelane_b32 v253, s14, 41
	s_lshl_b64 s[12:13], s[12:13], 17
	s_mul_hi_u32 s11, s10, 0x160
	v_writelane_b32 v253, s15, 42
	s_lshl_b64 s[14:15], s[18:19], 17
	s_add_u32 s12, s62, s12
	v_writelane_b32 v253, s62, 43
	s_addc_u32 s13, s63, s13
	s_add_u32 s14, s40, s14
	v_writelane_b32 v253, s63, 44
	s_addc_u32 s15, s44, s15
	v_writelane_b32 v253, s40, 45
	s_add_u32 s18, s12, 0x10000
	v_writelane_b32 v253, s44, 46
	s_addc_u32 s19, s13, 0
	v_writelane_b32 v253, s18, 47
	s_mul_i32 s11, s11, s5
	v_cvt_f32_i32_e32 v1, s7
	v_writelane_b32 v253, s19, 48
	s_add_u32 s18, s14, 0x10000
	v_writelane_b32 v253, s14, 49
	s_addc_u32 s19, s15, 0
	v_rcp_iflag_f32_e32 v3, v2
	v_writelane_b32 v253, s15, 50
	v_writelane_b32 v253, s18, 51
	s_add_u32 s14, s12, 0x10080
	v_mul_f32_e32 v3, v1, v3
	v_writelane_b32 v253, s19, 52
	v_writelane_b32 v253, s12, 53
	s_addc_u32 s15, s13, 0
	s_sub_i32 s11, 0x160, s11
	v_writelane_b32 v253, s13, 54
	s_sub_i32 s12, s11, s5
	s_cmp_ge_u32 s11, s5
	s_cselect_b32 s11, s12, s11
	s_sub_i32 s12, s11, s5
	s_cmp_ge_u32 s11, s5
	s_cselect_b32 s11, s12, s11
	s_sub_i32 s9, s9, s11
	s_abs_i32 s11, s9
	s_mul_hi_u32 s10, s11, s10
	s_mul_i32 s10, s10, s5
	s_sub_i32 s10, s11, s10
	s_ashr_i32 s9, s9, 31
	s_sub_i32 s11, s10, s5
	s_cmp_ge_u32 s10, s5
	s_cselect_b32 s10, s11, s10
	s_sub_i32 s11, s10, s5
	s_cmp_ge_u32 s10, s5
	s_cselect_b32 s5, s11, s10
	s_xor_b32 s5, s5, s9
	s_sub_i32 s12, s5, s9
	s_cmp_lt_i32 s12, 64
	v_writelane_b32 v253, s14, 55
	s_cselect_b64 s[10:11], -1, 0
	s_lshr_b32 s5, s12, 31
	v_writelane_b32 v253, s15, 56
	s_add_i32 s5, s12, s5
	v_writelane_b32 v253, s10, 57
	s_ashr_i32 s14, s5, 1
	s_and_b32 s9, s5, -2
	v_writelane_b32 v253, s11, 58
	s_mov_b32 s10, s14
	s_ashr_i32 s15, s14, 31
	v_writelane_b32 v253, s10, 59
	s_sub_i32 s18, s12, s9
	v_trunc_f32_e32 v3, v3
	v_writelane_b32 v253, s11, 60
	s_lshl_b64 s[10:11], s[14:15], 10
	s_add_u32 s5, s66, s10
	v_writelane_b32 v253, s66, 61
	s_mov_b32 s10, s18
	s_addc_u32 s9, s67, s11
	v_writelane_b32 v253, s67, 62
	s_ashr_i32 s19, s18, 31
	v_writelane_b32 v253, s10, 63
	v_fma_f32 v1, -v3, v2, v1
	s_sext_i32_i16 s2, s2
	v_writelane_b32 v254, s11, 0
	s_lshl_b64 s[10:11], s[18:19], 23
	s_add_u32 s10, s5, s10
	s_addc_u32 s11, s9, s11
	s_add_u32 s14, s10, 0x400000
	s_addc_u32 s15, s11, 0
	v_writelane_b32 v254, s14, 1
	s_movk_i32 s62, 0x3280
	s_mov_b32 s63, 0x24000
	v_writelane_b32 v254, s15, 2
	s_add_u32 s14, s10, 0x400080
	v_writelane_b32 v254, s10, 3
	s_addc_u32 s15, s11, 0
	s_ashr_i32 s9, s12, 31
	v_writelane_b32 v254, s11, 4
	v_writelane_b32 v254, s14, 5
	v_cmp_ge_f32_e64 s[10:11], |v1|, v2
	v_cvt_i32_f32_e32 v1, v3
	v_writelane_b32 v254, s15, 6
	v_writelane_b32 v254, s12, 7
	v_writelane_b32 v254, s9, 8
	s_load_dword s9, s[0:1], 0x130
	v_writelane_b32 v254, s36, 9
	s_ashr_i32 s5, s7, 30
	s_or_b32 s5, s5, 1
	v_writelane_b32 v254, s37, 10
	v_writelane_b32 v254, s6, 11
	s_mul_i32 s6, s27, s26
	s_waitcnt lgkmcnt(0)
	s_mul_i32 s6, s6, s9
	v_writelane_b32 v254, s6, 12
	s_and_b64 s[10:11], s[10:11], exec
	v_writelane_b32 v254, s4, 13
	v_writelane_b32 v254, s2, 14
	s_cselect_b32 s2, s5, 0
	v_readfirstlane_b32 s4, v1
	s_add_i32 s2, s4, s2
	s_mul_i32 s4, s2, s8
	s_sub_i32 s4, s7, s4
	s_sext_i32_i16 s4, s4
	s_add_i32 s3, s3, s4
	v_writelane_b32 v254, s3, 15
	s_sext_i32_i16 s2, s2
	s_ashr_i32 s97, s96, 31
	v_writelane_b32 v254, s2, 16
	s_lshl_b64 s[2:3], s[96:97], 11
	v_writelane_b32 v254, s2, 17
	v_mov_b32_e32 v1, 0
	v_mbcnt_lo_u32_b32 v2, -1, 0
	v_writelane_b32 v254, s3, 18
	s_lshl_b64 s[2:3], s[96:97], 12
	v_writelane_b32 v254, s2, 19
	v_cndmask_b32_e64 v225, 0, 1, s[36:37]
	v_mbcnt_hi_u32_b32 v232, -1, v2
	v_writelane_b32 v254, s3, 20
	s_add_u32 s2, s22, 0x11b10040
	s_addc_u32 s3, s23, 0
	v_writelane_b32 v254, s2, 21
	s_lshl_b32 s33, s26, 12
	v_mov_b32_e32 v244, v1
	v_writelane_b32 v254, s3, 22
	s_mul_i32 s2, s26, 0xd000
	s_mul_hi_i32 s3, s96, 0x1a00
	v_writelane_b32 v254, s2, 23
	v_mov_b32_e32 v245, v1
	v_mov_b32_e32 v246, v1
	v_writelane_b32 v254, s3, 24
	s_mul_i32 s2, s26, 0x3000
	s_mul_hi_i32 s3, s96, 0x600
	v_writelane_b32 v254, s2, 25
	v_mov_b32_e32 v247, v1
	s_nop 0
	v_writelane_b32 v254, s3, 26
	s_lshl_b32 s2, s43, 8
	v_writelane_b32 v254, s2, 27
	s_lshl_b32 s2, s26, 8
	v_writelane_b32 v254, s2, 28
	s_lshl_b32 s2, s43, 12
	v_writelane_b32 v254, s2, 29
	s_lshl_b64 s[2:3], s[96:97], 10
	v_writelane_b32 v254, s2, 30
	s_nop 1
	v_writelane_b32 v254, s3, 31
	s_add_u32 s2, s22, 0x1b4b0080
	s_addc_u32 s3, s23, 0
	v_writelane_b32 v254, s2, 32
	s_nop 1
	v_writelane_b32 v254, s3, 33
	s_mul_i32 s2, s26, 0x1800
	s_mul_hi_i32 s3, s96, 0x300
	v_writelane_b32 v254, s2, 34
	s_nop 1
	v_writelane_b32 v254, s3, 35
	s_lshl_b32 s2, s43, 11
	v_writelane_b32 v254, s2, 36
	s_lshl_b32 s2, s26, 11
	v_writelane_b32 v254, s2, 37
	s_lshl_b64 s[2:3], s[96:97], 9
	v_writelane_b32 v254, s2, 38
	s_nop 1
	v_writelane_b32 v254, s3, 39
	s_add_u32 s2, s22, 0x650000
	s_addc_u32 s3, s23, 0
	v_writelane_b32 v254, s2, 40
	s_ashr_i32 s71, s70, 31
	s_lshl_b64 s[68:69], s[70:71], 4
	v_writelane_b32 v254, s3, 41
	v_readfirstlane_b32 s2, v0
	s_lshl_b64 s[78:79], s[70:71], 6
	s_nop 0
	v_writelane_b32 v254, s2, 42
	s_add_i32 s2, 0, 0x20004
	v_writelane_b32 v254, s2, 43
	s_lshl_b64 s[2:3], s[70:71], 2
	v_writelane_b32 v254, s2, 44
	s_nop 1
	v_writelane_b32 v254, s3, 45
	s_lshl_b64 s[2:3], s[70:71], 3
	s_mov_b32 s71, s17
	s_load_dwordx16 s[4:19], s[0:1], 0x0
	v_writelane_b32 v254, s2, 46
	s_nop 1
	v_writelane_b32 v254, s3, 47
	s_waitcnt lgkmcnt(0)
	v_writelane_b32 v254, s4, 48
	s_nop 1
	v_writelane_b32 v254, s5, 49
	v_writelane_b32 v254, s6, 50
	v_writelane_b32 v254, s7, 51
	v_writelane_b32 v254, s8, 52
	v_writelane_b32 v254, s9, 53
	v_writelane_b32 v254, s10, 54
	v_writelane_b32 v254, s11, 55
	v_writelane_b32 v254, s12, 56
	v_writelane_b32 v254, s13, 57
	v_writelane_b32 v254, s14, 58
	v_writelane_b32 v254, s15, 59
	v_writelane_b32 v254, s16, 60
	v_writelane_b32 v254, s17, 61
	v_writelane_b32 v254, s18, 62
	v_writelane_b32 v254, s19, 63
	s_load_dwordx16 s[4:19], s[0:1], 0x40
	s_waitcnt lgkmcnt(0)
	v_writelane_b32 v255, s4, 0
	s_nop 1
	v_writelane_b32 v255, s5, 1
	v_writelane_b32 v255, s6, 2
	v_writelane_b32 v255, s7, 3
	v_writelane_b32 v255, s8, 4
	v_writelane_b32 v255, s9, 5
	v_writelane_b32 v255, s10, 6
	v_writelane_b32 v255, s11, 7
	v_writelane_b32 v255, s12, 8
	v_writelane_b32 v255, s13, 9
	v_writelane_b32 v255, s14, 10
	v_writelane_b32 v255, s15, 11
	v_writelane_b32 v255, s16, 12
	v_writelane_b32 v255, s17, 13
	v_writelane_b32 v255, s18, 14
	v_writelane_b32 v255, s19, 15
	s_load_dwordx16 s[4:19], s[0:1], 0x80
	s_waitcnt lgkmcnt(0)
	v_writelane_b32 v255, s4, 16
	s_nop 1
	v_writelane_b32 v255, s5, 17
	v_writelane_b32 v255, s6, 18
	v_writelane_b32 v255, s7, 19
	v_writelane_b32 v255, s8, 20
	v_writelane_b32 v255, s9, 21
	v_writelane_b32 v255, s10, 22
	v_writelane_b32 v255, s11, 23
	v_writelane_b32 v255, s12, 24
	v_writelane_b32 v255, s13, 25
	v_writelane_b32 v255, s14, 26
	v_writelane_b32 v255, s15, 27
	v_writelane_b32 v255, s16, 28
	v_writelane_b32 v255, s17, 29
	v_writelane_b32 v255, s18, 30
	v_writelane_b32 v255, s19, 31
	s_load_dwordx16 s[4:19], s[0:1], 0xc0
	s_waitcnt lgkmcnt(0)
	v_writelane_b32 v255, s4, 32
	s_nop 1
	v_writelane_b32 v255, s5, 33
	v_writelane_b32 v255, s6, 34
	v_writelane_b32 v255, s7, 35
	v_writelane_b32 v255, s8, 36
	v_writelane_b32 v255, s9, 37
	v_writelane_b32 v255, s10, 38
	v_writelane_b32 v255, s11, 39
	v_writelane_b32 v255, s12, 40
	v_writelane_b32 v255, s13, 41
	v_writelane_b32 v255, s14, 42
	v_writelane_b32 v255, s15, 43
	v_writelane_b32 v255, s16, 44
	v_writelane_b32 v255, s17, 45
	v_writelane_b32 v255, s18, 46
	v_writelane_b32 v255, s19, 47
	v_writelane_b32 v255, s57, 48
	v_writelane_b32 v255, s60, 49
	v_writelane_b32 v255, s58, 50
	v_writelane_b32 v255, s72, 51
	v_writelane_b32 v255, s73, 52
	v_writelane_b32 v255, s50, 53
	s_mov_b32 s4, 0
	v_writelane_b32 v255, s51, 54
	s_branch .LBB0_22

.LBB0_23:
	s_add_i32 s0, s24, -1
	s_mul_hi_i32 s1, s0, 0x2e8ba2e9
	s_lshr_b32 s2, s1, 31
	s_ashr_i32 s1, s1, 1
	s_add_i32 s30, s1, s2
	s_mul_i32 s1, s30, 11
	s_sub_i32 s21, s0, s1
	s_cmp_lt_i32 s21, 5
	s_mov_b64 s[0:1], -1
	s_cbranch_scc1 .LBB0_408
	s_mul_i32 s0, s30, 3
	s_mul_i32 s44, s30, 0x12000
	s_mul_hi_i32 s0, s0, 0x6000
	s_add_u32 s20, s42, s44
	s_addc_u32 s64, s71, s0
	s_cmp_lt_i32 s21, 8
	s_mov_b64 s[0:1], -1
	s_cbranch_scc1 .LBB0_125
	s_cmp_lt_i32 s21, 9
	s_cbranch_scc1 .LBB0_119
	s_cmp_lt_i32 s21, 10
	s_cbranch_scc1 .LBB0_105
	s_cmp_eq_u32 s21, 10
	s_cbranch_scc0 .LBB0_104
	s_cmp_eq_u32 s101, 1
	s_cbranch_scc0 .Lpk_entry_normal
	s_cmpk_lt_u32 s43, 0xc0
	s_cbranch_scc1 .Lpk_entry_normal
	s_cmpk_gt_u32 s43, 0xdf
	s_cbranch_scc1 .Lpk_entry_normal
	s_mov_b32 s101, 2
	s_sub_i32 s2, s43, 0xc0
	s_and_b32 s8, s2, 7
	s_add_i32 s8, s8, 40
	s_lshr_b32 s6, s2, 3
	s_add_i32 s6, s6, 18

	v_writelane_b32 v249, s6, 32
	v_writelane_b32 v249, s8, 33
	s_mov_b32 s7, 0
	s_lshl_b64 s[10:11], s[6:7], 19
	s_mov_b32 s9, 0
	s_lshl_b64 s[12:13], s[8:9], 19
	v_readlane_b32 s3, v249, 35
	s_add_u32 s10, s72, s10
	s_addc_u32 s11, s3, s11
	v_readlane_b32 s2, v251, 36
	v_readlane_b32 s3, v251, 37
	s_add_u32 s12, s2, s12
	s_addc_u32 s13, s3, s13
	v_writelane_b32 v249, s10, 42
	v_writelane_b32 v249, s11, 43
	v_writelane_b32 v249, s12, 38
	v_writelane_b32 v249, s13, 39
	s_add_u32 s2, s10, 0x40000
	s_addc_u32 s3, s11, 0
	v_writelane_b32 v249, s2, 36
	v_writelane_b32 v249, s3, 37
	s_add_u32 s2, s12, 0x40000
	s_addc_u32 s3, s13, 0
	v_writelane_b32 v249, s2, 40
	v_writelane_b32 v249, s3, 41
	s_add_u32 s2, s10, 0x40080
	s_addc_u32 s3, s11, 0
	v_writelane_b32 v249, s2, 44
	v_writelane_b32 v249, s3, 45

	s_mov_b64 s[0:1], -1
	s_branch .LBB0_105
.Lpk_entry_normal:
	v_readlane_b32 s0, v254, 9
	v_mov_b32_e32 v0, v224
	v_readlane_b32 s1, v254, 10
	s_andn2_b64 vcc, exec, s[0:1]
	v_readfirstlane_b32 s56, v0
	s_cbranch_vccnz .LBB0_48
	s_waitcnt vmcnt(0)
	v_lshlrev_b32_e32 v8, 4, v0
	v_add_u32_e32 v4, 0x2000, v8
	v_ashrrev_i32_e32 v2, 31, v4
	v_lshrrev_b32_e32 v2, 22, v2
	v_add_u32_e32 v2, v4, v2
	v_ashrrev_i32_e32 v3, 10, v2
	v_mul_i32_i24_e32 v5, 0x400, v3
	v_sub_u32_e32 v4, v4, v5
	v_lshrrev_b32_e32 v5, 4, v4
	v_bitop3_b32 v4, v5, v4, 32 bitop3:0x6c
	v_ashrrev_i32_e32 v5, 31, v4
	v_lshrrev_b32_e32 v5, 26, v5
	v_add_u32_e32 v6, v4, v5
	v_bfe_i32 v9, v0, 27, 1
	v_ashrrev_i32_e32 v5, 6, v6
	v_and_b32_e32 v6, 0xc0, v6
	v_lshrrev_b32_e32 v9, 22, v9
	v_sub_u32_e32 v4, v4, v6
	v_lshlrev_b32_e32 v6, 3, v3
	v_add_u32_e32 v9, v8, v9
	v_and_b32_e32 v6, 0xfffff0, v6
	v_and_b32_e32 v9, 0xfffffc00, v9
	v_lshlrev_b32_e32 v2, 5, v3
	v_add_u32_e32 v6, v5, v6
	s_movk_i32 s1, 0xb00
	v_sub_u32_e32 v8, v8, v9
	v_and_b32_e32 v2, 32, v2
	v_ashrrev_i16_sdwa v4, v228, sext(v4) dst_sel:DWORD dst_unused:UNUSED_PAD src0_sel:DWORD src1_sel:BYTE_0
	v_mul_lo_u32 v6, v6, s1
	v_lshrrev_b32_e32 v9, 4, v8
	v_bfe_i32 v4, v4, 0, 16
	v_or_b32_e32 v6, v6, v2
	v_bitop3_b32 v8, v9, v8, 32 bitop3:0x6c
	v_add_lshl_u32 v146, v6, v4, 1
	v_ashrrev_i32_e32 v6, 31, v0
	v_ashrrev_i32_e32 v9, 31, v8
	v_lshrrev_b32_e32 v6, 26, v6
	v_lshrrev_b32_e32 v9, 26, v9
	v_add_u32_e32 v6, v0, v6
	v_add_u32_e32 v10, v8, v9
	v_ashrrev_i32_e32 v7, 6, v6
	v_ashrrev_i32_e32 v9, 6, v10
	v_and_b32_e32 v10, 0xc0, v10
	v_sub_u32_e32 v8, v8, v10
	v_lshlrev_b32_e32 v10, 3, v7
	v_and_b32_e32 v10, 0xfffff0, v10
	s_ashr_i32 s0, s56, 6
	v_lshlrev_b32_e32 v6, 5, v7
	v_add_u32_e32 v10, v9, v10
	s_lshl_b32 s45, s0, 10
	v_and_b32_e32 v6, 32, v6
	v_ashrrev_i16_sdwa v8, v228, sext(v8) dst_sel:DWORD dst_unused:UNUSED_PAD src0_sel:DWORD src1_sel:BYTE_0
	v_mul_lo_u32 v10, v10, s1
	v_bfe_i32 v8, v8, 0, 16
	v_or_b32_e32 v10, v10, v6
	s_add_i32 s51, s45, 0
	v_readlane_b32 s2, v249, 23
	v_add_lshl_u32 v148, v10, v8, 1
	s_add_i32 m0, s51, 0x10000
	v_readlane_b32 s3, v249, 24
	s_add_i32 s52, s51, 0x2000
	s_add_i32 s53, s51, 0x4000
	s_add_i32 s59, s51, 0x6000
	s_ashr_i32 s1, s56, 8
	s_mov_b32 s5, s20
	global_load_lds_dwordx4 v148, s[2:3]
	s_add_i32 m0, s51, 0x12000
	s_mov_b32 s55, s31
	global_load_lds_dwordx4 v146, s[2:3]
	v_readlane_b32 s2, v249, 19
	s_mov_b32 m0, s51
	v_readlane_b32 s3, v249, 20
	s_mov_b32 s31, s21
	s_nop 3
	global_load_lds_dwordx4 v148, s[2:3]
	s_mov_b32 m0, s52
	s_nop 0
	global_load_lds_dwordx4 v146, s[2:3]
	v_readlane_b32 s2, v249, 17
	s_add_i32 m0, s51, 0x14000
	v_readlane_b32 s3, v249, 18
	s_nop 4
	global_load_lds_dwordx4 v148, s[2:3]
	s_add_i32 m0, s51, 0x16000
	s_cmp_lg_u32 s1, 1
	global_load_lds_dwordx4 v146, s[2:3]
	v_readlane_b32 s2, v249, 21
	s_mov_b32 m0, s53
	v_readlane_b32 s3, v249, 22
	s_nop 4
	global_load_lds_dwordx4 v148, s[2:3]
	s_mov_b32 m0, s59
	s_nop 0
	global_load_lds_dwordx4 v146, s[2:3]
	s_cbranch_scc1 .LBB0_31
	s_barrier

.LBB0_40:
	s_cmp_eq_u32 s50, 32
	s_cbranch_scc1 .Lpk_wait

.Lpk_wait:
	s_cmp_eq_u32 s101, 1
	s_cbranch_scc0 .Lpk_wait_ret
	s_and_b32 s2, s43, 7
	s_mul_i32 s2, s2, 24
	s_lshr_b32 s3, s43, 3
	s_add_i32 s2, s2, s3
	s_cmpk_lt_u32 s2, 0xa0
	s_cbranch_scc1 .Lpk_wait_ret
	v_readlane_b32 s2, v251, 54
	v_readlane_b32 s3, v251, 55
	s_add_u32 s2, s2, 0x3600
	s_addc_u32 s3, s3, 0
	s_add_i32 s16, s30, 1
	s_lshl_b32 s16, s16, 5
	s_mov_b32 s17, 0
.Lpk_spin:
	global_load_dword v0, v1, s[2:3] sc1
	s_waitcnt vmcnt(0)
	v_readfirstlane_b32 s14, v0
	s_cmp_ge_u32 s14, s16
	s_cbranch_scc1 .Lpk_spin_done
	s_sleep 4
	s_add_i32 s17, s17, 1
	s_cmpk_lt_u32 s17, 0x200
	s_cbranch_scc1 .Lpk_spin
.Lpk_spin_done:
	buffer_inv sc1
	s_waitcnt vmcnt(0)
	s_branch .Lpk_wait_ret

.LBB0_48:
	s_cmp_lt_i32 s24, 34
	v_readlane_b32 s2, v249, 27
	s_cselect_b64 s[0:1], -1, 0
	v_readlane_b32 s3, v249, 28
	s_and_b64 s[0:1], s[2:3], s[0:1]
	v_readlane_b32 s2, v251, 48
	v_readlane_b32 s3, v251, 49
	s_and_b64 s[0:1], s[2:3], s[0:1]
	s_andn2_b64 vcc, exec, s[0:1]
	s_cbranch_vccnz .LBB0_104
	s_cmp_eq_u32 s101, 1
	s_cbranch_scc0 .Lcw_gate_done
	s_cmp_lg_u32 s27, 0
	s_cbranch_scc1 .Lcw_gate_bar
	v_readlane_b32 s2, v251, 54
	v_readlane_b32 s3, v251, 55
	s_add_u32 s2, s2, 0x3600
	s_addc_u32 s3, s3, 0
	s_add_i32 s6, s30, 1
	s_lshl_b32 s6, s6, 5
	s_mov_b32 s7, 0
.Lcw_gate_spin:
	global_load_dword v0, v1, s[2:3] sc1
	s_waitcnt vmcnt(0)
	v_readfirstlane_b32 s8, v0
	s_cmp_ge_u32 s8, s6
	s_cbranch_scc1 .Lcw_gate_bar
	s_sleep 8
	s_add_i32 s7, s7, 1
	s_cmpk_lt_u32 s7, 0x200
	s_cbranch_scc1 .Lcw_gate_spin

.Lcw_gate_done:
	v_readlane_b32 s0, v249, 29
	s_add_i32 s0, s27, s0
	s_cmpk_gt_i32 s0, 0xcff
	s_cbranch_scc1 .LBB0_104
	s_mul_i32 s1, s27, 0x2200
	s_add_i32 s8, s0, 0x13e0
	s_add_i32 s0, s30, 1
	s_add_i32 s5, s1, 0
	s_ashr_i32 s1, s0, 31
	s_mul_i32 s10, s0, 0x1600000
	s_lshl_b64 s[2:3], s[0:1], 22
	s_lshl_b64 s[6:7], s[0:1], 23
	s_lshl_b64 s[12:13], s[0:1], 20
	s_lshl_b64 s[14:15], s[0:1], 24
	s_mov_b32 s39, s21
	s_mov_b32 s40, s20
	v_readlane_b32 s16, v249, 0
	s_waitcnt vmcnt(0)
	v_lshlrev_b32_e32 v7, 3, v204
	s_mul_hi_i32 s9, s0, 0x1600000
	s_mul_hi_i32 s11, s0, 0x120000
	s_mul_i32 s36, s0, 0x120000
	s_mul_hi_i32 s37, s0, 0xca0000
	s_mul_i32 s38, s0, 0xca0000
	v_readlane_b32 s17, v249, 1
	s_add_u32 s0, s16, s10
	v_and_b32_e32 v20, 31, v240
	v_lshrrev_b32_e32 v3, 3, v204
	v_and_b32_e32 v22, 56, v7
	v_readlane_b32 s18, v249, 2
	v_readlane_b32 s19, v249, 3
	v_readlane_b32 s20, v249, 4
	v_readlane_b32 s21, v249, 5
	v_readlane_b32 s22, v249, 6
	v_readlane_b32 s23, v249, 7
	s_addc_u32 s1, s17, s9
	v_lshlrev_b32_e32 v0, 2, v20
	v_mul_u32_u24_e32 v7, 0x84, v22
	v_lshlrev_b32_e32 v8, 2, v3
	s_mov_b32 s54, s26
	v_lshl_add_u64 v[4:5], s[0:1], 0, v[0:1]
	v_add_u32_e32 v6, s5, v0
	v_add3_u32 v7, s5, v7, v8
	s_mov_b64 s[52:53], s[24:25]
	s_mov_b64 s[0:1], s[28:29]
	s_mov_b32 s5, s27
	s_mov_b32 s10, s30
	s_mov_b32 s9, s31
	v_readlane_b32 s16, v255, 32
	v_readlane_b32 s28, v255, 44
	v_readlane_b32 s29, v255, 45
	v_readlane_b32 s30, v255, 46
	v_readlane_b32 s31, v255, 47
	s_mov_b64 s[28:29], s[0:1]
	s_add_u32 s0, s30, s2
	v_readlane_b32 s24, v255, 40
	s_addc_u32 s1, s31, s3
	v_readlane_b32 s25, v255, 41
	s_mov_b32 s31, s9
	s_add_u32 s9, s24, s6
	v_readlane_b32 s20, v255, 36
	s_mov_b32 s30, s10
	s_addc_u32 s10, s25, s7
	v_readlane_b32 s21, v255, 37
	v_lshl_add_u64 v[8:9], s[0:1], 0, v[0:1]
	s_add_u32 s0, s20, s12
	v_readlane_b32 s80, v255, 0
	s_addc_u32 s1, s21, s13
	v_readlane_b32 s94, v255, 14
	v_lshl_add_u64 v[10:11], s[0:1], 0, v[0:1]
	v_readlane_b32 s95, v255, 15
	s_add_u32 s0, s94, s12
	v_readlane_b32 s92, v255, 12
	s_addc_u32 s1, s95, s13
	v_readlane_b32 s93, v255, 13
	v_lshl_add_u64 v[12:13], s[0:1], 0, v[0:1]
	s_add_u32 s0, s92, s36
	v_or_b32_e32 v14, 8, v3
	v_or_b32_e32 v15, 16, v3
	s_addc_u32 s1, s93, s11
	v_lshlrev_b32_e32 v31, 11, v14
	v_lshlrev_b32_e32 v32, 11, v15
	v_readlane_b32 s26, v255, 42
	v_lshlrev_b32_e32 v35, 10, v14
	v_lshlrev_b32_e32 v36, 10, v15
	v_lshlrev_b32_e32 v39, 9, v14
	v_lshlrev_b32_e32 v40, 9, v15
	v_lshl_add_u64 v[14:15], s[0:1], 0, v[0:1]
	s_movk_i32 s0, 0x300
	v_readlane_b32 s27, v255, 43
	v_mad_u32_u24 v43, v3, s0, v229
	v_mad_u32_u24 v44, v3, s0, v236
	v_mad_u32_u24 v45, v3, s0, v237
	s_add_u32 s0, s26, s14
	v_or_b32_e32 v16, 24, v3
	v_readlane_b32 s86, v255, 6
	s_addc_u32 s1, s27, s15
	v_lshlrev_b32_e32 v33, 11, v16
	v_lshlrev_b32_e32 v37, 10, v16
	v_readlane_b32 s87, v255, 7
	v_lshlrev_b32_e32 v41, 9, v16
	v_lshl_add_u64 v[16:17], s[0:1], 0, v[0:1]
	s_add_u32 s0, s86, s38
	v_lshrrev_b32_e32 v2, 5, v204
	s_mov_b64 s[24:25], s[52:53]
	s_addc_u32 s1, s87, s37
	v_lshlrev_b32_e32 v30, 11, v3
	v_lshlrev_b32_e32 v34, 10, v3
	s_mov_b32 s20, s40
	s_mov_b32 s21, s39
	v_lshlrev_b32_e32 v38, 9, v3
	v_mul_u32_u24_e32 v42, 0x300, v3
	s_mov_b32 s27, s5
	s_mov_b32 s26, s54
	v_lshl_add_u64 v[18:19], s[0:1], 0, v[0:1]
	v_mov_b32_e32 v3, v2
	v_lshlrev_b32_e32 v20, 2, v20
	v_lshlrev_b32_e32 v22, 1, v22
	v_readlane_b32 s17, v255, 33
	v_readlane_b32 s18, v255, 34
	v_readlane_b32 s19, v255, 35
	v_readlane_b32 s22, v255, 38
	v_readlane_b32 s23, v255, 39
	v_readlane_b32 s81, v255, 1
	v_readlane_b32 s82, v255, 2
	v_readlane_b32 s83, v255, 3
	v_readlane_b32 s84, v255, 4
	v_readlane_b32 s85, v255, 5
	v_readlane_b32 s88, v255, 8
	v_readlane_b32 s89, v255, 9
	v_readlane_b32 s90, v255, 10
	v_readlane_b32 s91, v255, 11
	s_branch .LBB0_52

.LBB0_110:
	s_add_i32 s67, s67, 1
	s_mul_i32 s7, s67, s60
	s_mul_hi_u32 s9, s67, s26
	s_add_i32 s9, s9, s7
	s_mul_i32 s7, s67, s26
	s_add_u32 s10, s7, s43
	s_addc_u32 s11, s9, s57
	s_cmp_eq_u32 s101, 2
	s_cbranch_scc0 .Lpj_l_ok
	s_mov_b32 s10, 0x10000
	s_mov_b32 s11, 0
.Lpj_l_ok:
	s_cmp_eq_u32 s101, 0
	s_movk_i32 s6, 0x41f
	s_cselect_b32 s6, s6, 0x3ff
	v_mov_b32_e32 v2, s6
	v_mov_b32_e32 v3, 0
	v_cmp_gt_i64_e64 s[36:37], s[10:11], v[2:3]
	s_and_b64 vcc, exec, s[36:37]
	s_cbranch_vccnz .LBB0_112
	s_ashr_i32 s6, s10, 31
	s_lshr_b32 s6, s6, 29
	s_add_i32 s6, s10, s6
	s_ashr_i32 s7, s6, 3
	s_and_b32 s6, s6, -8
	s_sub_i32 s6, s10, s6
	s_cmp_lt_i32 s6, 0
	s_movk_i32 s8, 0x85
	s_cselect_b32 s8, s8, 0x84
	s_cmp_eq_u32 s101, 0
	s_cselect_b32 s8, s8, 0x80
	s_mul_i32 s6, s8, s6
	s_add_i32 s6, s6, s7
	s_mul_hi_i32 s7, s6, 0x2e8ba2e9
	s_lshr_b32 s8, s7, 31
	s_ashr_i32 s7, s7, 5
	s_add_i32 s7, s7, s8
	s_lshl_b32 s8, s7, 3
	s_sub_i32 s9, 48, s8
	s_min_i32 s9, s9, 8
	s_abs_i32 s12, s9
	v_cvt_f32_u32_e32 v2, s12
	s_sub_i32 s16, 0, s12
	s_mulk_i32 s7, 0xb0
	s_sub_i32 s7, s6, s7
	v_rcp_iflag_f32_e32 v2, v2
	s_abs_i32 s6, s7
	s_xor_b32 s13, s7, s9
	s_ashr_i32 s13, s13, 31
	v_mul_f32_e32 v2, 0x4f7ffffe, v2
	v_cvt_u32_f32_e32 v2, v2
	s_nop 0
	v_readfirstlane_b32 s17, v2
	s_mul_i32 s16, s16, s17
	s_mul_hi_u32 s16, s17, s16
	s_add_i32 s17, s17, s16
	s_mul_hi_u32 s16, s6, s17
	s_mul_i32 s17, s16, s12
	s_sub_i32 s6, s6, s17
	s_add_i32 s34, s16, 1
	s_sub_i32 s17, s6, s12
	s_cmp_ge_u32 s6, s12
	s_cselect_b32 s16, s34, s16
	s_cselect_b32 s6, s17, s6
	s_add_i32 s17, s16, 1
	s_cmp_ge_u32 s6, s12
	s_cselect_b32 s6, s17, s16
	s_xor_b32 s6, s6, s13
	s_sub_i32 s6, s6, s13
	s_mul_i32 s9, s6, s9
	s_sub_i32 s7, s7, s9
	s_add_i32 s8, s7, s8
.LBB0_112:
	s_cmp_eq_u32 s101, 0
	s_movk_i32 s9, 0x420
	s_cselect_b32 s9, s9, 0x400
	v_mov_b32_e32 v2, s9
	v_mov_b32_e32 v3, 0
	s_ashr_i32 s9, s8, 31
	v_cmp_lt_i64_e32 vcc, s[10:11], v[2:3]
	s_lshl_b64 s[10:11], s[8:9], 19
	v_readlane_b32 s12, v251, 36
	v_readlane_b32 s13, v251, 37
	s_add_u32 s10, s12, s10
	s_addc_u32 s11, s13, s11
	s_and_b64 s[12:13], vcc, exec
	s_cselect_b32 s9, s11, s15
	s_cselect_b32 s49, s10, s14
	s_ashr_i32 s7, s6, 31
	s_lshl_b64 s[12:13], s[6:7], 19
	s_add_u32 s12, s72, s12
	v_readlane_b32 s7, v249, 35
	s_addc_u32 s13, s7, s13
	s_and_b64 s[16:17], vcc, exec
	s_cselect_b32 s7, s13, s3
	s_cselect_b32 s54, s12, s2
	s_add_u32 s14, s14, 0x40080
	s_addc_u32 s15, s15, 0
	s_add_u32 s55, s2, 0x100
	v_mov_b32_e32 v2, 0
	s_addc_u32 s50, s3, 0
	s_mov_b32 s56, -2
	v_mov_b32_e32 v3, v2
	v_mov_b32_e32 v4, v2
	v_mov_b32_e32 v5, v2
	v_mov_b32_e32 v10, v2
	v_mov_b32_e32 v11, v2
	v_mov_b32_e32 v12, v2
	v_mov_b32_e32 v13, v2
	v_mov_b32_e32 v18, v2
	v_mov_b32_e32 v19, v2
	v_mov_b32_e32 v20, v2
	v_mov_b32_e32 v21, v2
	v_mov_b32_e32 v26, v2
	v_mov_b32_e32 v27, v2
	v_mov_b32_e32 v28, v2
	v_mov_b32_e32 v29, v2
	v_mov_b32_e32 v34, v2
	v_mov_b32_e32 v35, v2
	v_mov_b32_e32 v36, v2
	v_mov_b32_e32 v37, v2
	v_mov_b32_e32 v42, v2
	v_mov_b32_e32 v43, v2
	v_mov_b32_e32 v44, v2
	v_mov_b32_e32 v45, v2
	v_mov_b32_e32 v50, v2
	v_mov_b32_e32 v51, v2
	v_mov_b32_e32 v52, v2
	v_mov_b32_e32 v53, v2
	v_mov_b32_e32 v58, v2
	v_mov_b32_e32 v59, v2
	v_mov_b32_e32 v60, v2
	v_mov_b32_e32 v61, v2
	v_mov_b32_e32 v6, v2
	v_mov_b32_e32 v7, v2
	v_mov_b32_e32 v8, v2
	v_mov_b32_e32 v9, v2
	v_mov_b32_e32 v14, v2
	v_mov_b32_e32 v15, v2
	v_mov_b32_e32 v16, v2
	v_mov_b32_e32 v17, v2
	v_mov_b32_e32 v22, v2
	v_mov_b32_e32 v23, v2
	v_mov_b32_e32 v24, v2
	v_mov_b32_e32 v25, v2
	v_mov_b32_e32 v30, v2
	v_mov_b32_e32 v31, v2
	v_mov_b32_e32 v32, v2
	v_mov_b32_e32 v33, v2
	v_mov_b32_e32 v38, v2
	v_mov_b32_e32 v39, v2
	v_mov_b32_e32 v40, v2
	v_mov_b32_e32 v41, v2
	v_mov_b32_e32 v46, v2
	v_mov_b32_e32 v47, v2
	v_mov_b32_e32 v48, v2
	v_mov_b32_e32 v49, v2
	v_mov_b32_e32 v54, v2
	v_mov_b32_e32 v55, v2
	v_mov_b32_e32 v56, v2
	v_mov_b32_e32 v57, v2
	v_mov_b32_e32 v62, v2
	v_mov_b32_e32 v63, v2
	v_mov_b32_e32 v64, v2
	v_mov_b32_e32 v65, v2
	v_mov_b32_e32 v66, v2
	v_mov_b32_e32 v67, v2
	v_mov_b32_e32 v68, v2
	v_mov_b32_e32 v69, v2
	v_mov_b32_e32 v74, v2
	v_mov_b32_e32 v75, v2
	v_mov_b32_e32 v76, v2
	v_mov_b32_e32 v77, v2
	v_mov_b32_e32 v82, v2
	v_mov_b32_e32 v83, v2
	v_mov_b32_e32 v84, v2
	v_mov_b32_e32 v85, v2
	v_mov_b32_e32 v90, v2
	v_mov_b32_e32 v91, v2
	v_mov_b32_e32 v92, v2
	v_mov_b32_e32 v93, v2
	v_mov_b32_e32 v98, v2
	v_mov_b32_e32 v99, v2
	v_mov_b32_e32 v100, v2
	v_mov_b32_e32 v101, v2
	v_mov_b32_e32 v106, v2
	v_mov_b32_e32 v107, v2
	v_mov_b32_e32 v108, v2
	v_mov_b32_e32 v109, v2
	v_mov_b32_e32 v114, v2
	v_mov_b32_e32 v115, v2
	v_mov_b32_e32 v116, v2
	v_mov_b32_e32 v117, v2
	v_mov_b32_e32 v122, v2
	v_mov_b32_e32 v123, v2
	v_mov_b32_e32 v124, v2
	v_mov_b32_e32 v125, v2
	v_mov_b32_e32 v70, v2
	v_mov_b32_e32 v71, v2
	v_mov_b32_e32 v72, v2
	v_mov_b32_e32 v73, v2
	v_mov_b32_e32 v78, v2
	v_mov_b32_e32 v79, v2
	v_mov_b32_e32 v80, v2
	v_mov_b32_e32 v81, v2
	v_mov_b32_e32 v86, v2
	v_mov_b32_e32 v87, v2
	v_mov_b32_e32 v88, v2
	v_mov_b32_e32 v89, v2
	v_mov_b32_e32 v94, v2
	v_mov_b32_e32 v95, v2
	v_mov_b32_e32 v96, v2
	v_mov_b32_e32 v97, v2
	v_mov_b32_e32 v102, v2
	v_mov_b32_e32 v103, v2
	v_mov_b32_e32 v104, v2
	v_mov_b32_e32 v105, v2
	v_mov_b32_e32 v110, v2
	v_mov_b32_e32 v111, v2
	v_mov_b32_e32 v112, v2
	v_mov_b32_e32 v113, v2
	v_mov_b32_e32 v118, v2
	v_mov_b32_e32 v119, v2
	v_mov_b32_e32 v120, v2
	v_mov_b32_e32 v121, v2
	v_mov_b32_e32 v126, v2
	v_mov_b32_e32 v127, v2
	v_mov_b32_e32 v128, v2
	v_mov_b32_e32 v129, v2

.LBB0_118:
	s_cmp_eq_u32 s101, 2
	s_cbranch_scc0 .Lpj_exit_normal
	s_cmp_lg_u32 s27, 0
	s_cbranch_scc1 .Lpj_sig_done
	buffer_wbl2 sc1
	s_waitcnt vmcnt(0)
	v_readlane_b32 s2, v251, 54
	v_readlane_b32 s3, v251, 55
	s_add_u32 s2, s2, 0x3600
	s_addc_u32 s3, s3, 0
	s_mov_b64 s[6:7], exec
	s_mov_b64 exec, 1
	v_mov_b32_e32 v2, 1
	global_atomic_add v1, v2, s[2:3]
	s_mov_b64 exec, s[6:7]
	s_waitcnt vmcnt(0)
.Lpj_sig_done:
	s_and_b32 s2, s43, 7
	s_lshl_b32 s2, s2, 7
	s_lshr_b32 s3, s43, 3
	s_add_i32 s2, s2, s3
	s_mul_hi_i32 s7, s2, 0x2e8ba2e9
	s_ashr_i32 s7, s7, 5
	s_mul_i32 s3, s7, 0xb0
	s_sub_i32 s2, s2, s3
	s_and_b32 s8, s2, 7
	s_lshl_b32 s7, s7, 3
	s_add_i32 s8, s8, s7
	s_lshr_b32 s6, s2, 3

	v_writelane_b32 v249, s6, 32
	v_writelane_b32 v249, s8, 33
	s_mov_b32 s7, 0
	s_lshl_b64 s[10:11], s[6:7], 19
	s_mov_b32 s9, 0
	s_lshl_b64 s[12:13], s[8:9], 19
	v_readlane_b32 s3, v249, 35
	s_add_u32 s10, s72, s10
	s_addc_u32 s11, s3, s11
	v_readlane_b32 s2, v251, 36
	v_readlane_b32 s3, v251, 37
	s_add_u32 s12, s2, s12
	s_addc_u32 s13, s3, s13
	v_writelane_b32 v249, s10, 42
	v_writelane_b32 v249, s11, 43
	v_writelane_b32 v249, s12, 38
	v_writelane_b32 v249, s13, 39
	s_add_u32 s2, s10, 0x40000
	s_addc_u32 s3, s11, 0
	v_writelane_b32 v249, s2, 36
	v_writelane_b32 v249, s3, 37
	s_add_u32 s2, s12, 0x40000
	s_addc_u32 s3, s13, 0
	v_writelane_b32 v249, s2, 40
	v_writelane_b32 v249, s3, 41
	s_add_u32 s2, s10, 0x40080
	s_addc_u32 s3, s11, 0
	v_writelane_b32 v249, s2, 44
	v_writelane_b32 v249, s3, 45

	s_mov_b32 s101, 1
	s_branch .LBB0_48
